# fused-LN epilogue residual loads flat->global with counted waits; L8 loop-invariant subln_g load hoisted; diff-attention tile loop: Q re-fetch as global loads with counted wait (no longer waits on nex
# speedup vs baseline: 1.0198x; 1.0076x over previous
; #define LAS __attribute__((address_space(3)))
; #define AT_LOAD_K(jt) do { const bf16_t* kp_ = Kp + (size_t)((jt) * 64 + krow) * ldk + kc16 * 8; sk0 = *(const bf16x8*)kp_; sk1 = *(const bf16x8*)(kp_ + 64); } while (0)
; #define AT_LOAD_V(jt, half) do { const bf16_t* vp_ = Vtp + (size_t)(vrow + 128 * (half)) * ldv + (jt) * 64 + vc * 8; sv0 = *(const bf16x8*)vp_; sv1 = *(const bf16x8*)(vp_ + 32); } while (0)
; template <int MODE, int DV> ...
;     ...
;     const bool pre = jt + 1 < jt_hi;
;     bf16x8 qx[4];
;     if (DV == 256) { const bf16_t* q2 = qlane; asm volatile("" : "+v"(q2));
; #pragma unroll
;       for (int u = 0; u < 4; ++u) qx[u] = *(const bf16x8*)(q2 + (4 + u) * 16); }
;     if (pre) { AT_LOAD_K(jt + 1); AT_LOAD_V(jt + 1, 0); }
;     const int kb = jt * 64;
;     u64 allow;
;     if (MODE == M_CAUSAL) allow = cmask(tq - kb + 1);
;     else if (MODE == M_WINDOW) allow = cmask(tq - kb + 1) & ~cmask(tq - 512 - kb + 1);
;     else if (MODE == M_BITS) allow = mk[(size_t)(wid * 32 + r32) * 64 + jt] & cmask(tq - kb + 1);
;     else if (MODE == M_SLC) allow = ((selw >> jt) & 1ull) ? cmask(tq - kb + 1) : 0ull;
;     else allow = cmask(tcmp - kb + 1);
;     const bool act = MODE == M_CMP || __any(allow != 0ull);
;     bf16x8 pa[4];
;     if (act) {
;       const LAS unsigned char* Kb = lds + cur * 17408 + r32 * 272 + hi * 16;
;       f32x16 p0 = {}, p1 = {};
; #pragma unroll
;       for (int db = 0; db < 8; db += KBAT) { bf16x8 ka[KBAT], kc[KBAT];
; #pragma unroll
;         for (int u = 0; u < KBAT; ++u) { ka[u] = *(const LAS bf16x8*)(Kb + (db + u) * 32); kc[u] = *(const LAS bf16x8*)(Kb + 32 * 272 + (db + u) * 32); }
;         __builtin_amdgcn_sched_barrier(0);
; #pragma unroll
;         for (int u = 0; u < KBAT; ++u) { const int d0 = db + u; const bf16x8 qf = d0 < NQR ? qr[d0 < NQR ? d0 : 0] : qx[d0 >= NQR ? d0 - NQR : 0];
;           p0 = __builtin_amdgcn_mfma_f32_32x32x16_bf16(ka[u], qf, p0, 0, 0, 0);
;           p1 = __builtin_amdgcn_mfma_f32_32x32x16_bf16(kc[u], qf, p1, 0, 0, 0); }
;         __builtin_amdgcn_sched_barrier(0); }
.LBB0_1419:
	v_mov_b64_e32 v[146:147], v[214:215]
	s_waitcnt vmcnt(0)
	global_load_dwordx4 v[206:209], v[146:147], off offset:128
	global_load_dwordx4 v[202:205], v[146:147], off offset:160
	global_load_dwordx4 v[198:201], v[146:147], off offset:192
	global_load_dwordx4 v[194:197], v[146:147], off offset:224
	s_add_i32 s2, s19, 0x41
	s_cmp_ge_u32 s2, s18
	s_cselect_b64 s[10:11], -1, 0
	s_cmp_lt_u32 s2, s18
	s_cselect_b64 s[2:3], -1, 0
	s_and_b64 vcc, exec, s[10:11]
	s_cbranch_vccnz .LBB0_1421
	v_add_u32_e32 v146, s72, v226
	v_mad_i64_i32 v[146:147], s[4:5], v146, s33, v[222:223]
	global_load_dwordx4 v[178:181], v[146:147], off
	global_load_dwordx4 v[182:185], v[146:147], off offset:128
	v_lshl_add_u64 v[146:147], s[72:73], 1, v[216:217]
	global_load_dwordx4 v[186:189], v[146:147], off
	global_load_dwordx4 v[190:193], v[146:147], off offset:64
.LBB0_1421:
	v_add_u32_e32 v146, 1, v237
	v_lshlrev_b64 v[146:147], v146, -1
	v_not_b32_e32 v147, v147
	v_not_b32_e32 v146, v146
	v_cmp_lt_i32_e32 vcc, -1, v237
	v_cmp_lt_i32_e64 s[4:5], 62, v237
	s_nop 0
	v_cndmask_b32_e32 v146, 0, v146, vcc
	v_cndmask_b32_e32 v147, 0, v147, vcc
	v_cndmask_b32_e64 v225, v147, -1, s[4:5]
	v_cndmask_b32_e64 v224, v146, -1, s[4:5]
	v_cmp_ne_u64_e32 vcc, 0, v[224:225]
	s_cmp_lg_u64 vcc, 0
	v_cndmask_b32_e64 v146, 0, 1, s[2:3]
	s_cselect_b64 s[12:13], -1, 0
	v_cmp_ne_u32_e64 s[2:3], 1, v146
	s_cbranch_vccz .LBB0_1432
	s_mul_i32 s20, s16, 0x4400
	v_add_u32_e32 v221, s20, v232
	ds_read_b128 v[130:133], v221
	ds_read_b128 v[134:137], v221 offset:8704
	v_mov_b32_e32 v239, 0x358637bd
	s_waitcnt lgkmcnt(0)
	v_mfma_f32_32x32x16_bf16 v[146:161], v[130:133], v[162:165], 0
	v_mfma_f32_32x32x16_bf16 v[130:145], v[134:137], v[162:165], 0
	ds_read_b128 v[210:213], v221 offset:32
	ds_read_b128 v[240:243], v221 offset:8736
	s_waitcnt lgkmcnt(0)
	v_mfma_f32_32x32x16_bf16 v[146:161], v[210:213], v[166:169], v[146:161]
	v_mfma_f32_32x32x16_bf16 v[130:145], v[240:243], v[166:169], v[130:145]
	ds_read_b128 v[210:213], v221 offset:64
	ds_read_b128 v[240:243], v221 offset:8768
	s_waitcnt lgkmcnt(0)
	v_mfma_f32_32x32x16_bf16 v[146:161], v[210:213], v[170:173], v[146:161]
	v_mfma_f32_32x32x16_bf16 v[130:145], v[240:243], v[170:173], v[130:145]
	ds_read_b128 v[210:213], v221 offset:96
	ds_read_b128 v[240:243], v221 offset:8800
	s_waitcnt lgkmcnt(0)
	v_mfma_f32_32x32x16_bf16 v[146:161], v[210:213], v[174:177], v[146:161]
	v_mfma_f32_32x32x16_bf16 v[130:145], v[240:243], v[174:177], v[130:145]
	ds_read_b128 v[210:213], v221 offset:128
	ds_read_b128 v[240:243], v221 offset:8832
	s_waitcnt lgkmcnt(0)
	s_cmp_lg_u64 s[10:11], 0
	s_cbranch_scc1 .Lcq_w0
	s_waitcnt vmcnt(4)
	s_branch .Lcq_w1

; #define LAS __attribute__((address_space(3)))
; #define AT_WRITE_K(buf) do { LAS unsigned char* kb_ = lds + (buf) * 17408 + krow * 272 + kc16 * 16; *(LAS bf16x8*)kb_ = sk0; *(LAS bf16x8*)(kb_ + 128) = sk1; } while (0)
; template <int MODE, int DV> ...
;     ...
;       for (int db = 0; db < 8; db += KBAT) { bf16x8 ka[KBAT], kc[KBAT];
; #pragma unroll
;         for (int u = 0; u < KBAT; ++u) { ka[u] = *(const LAS bf16x8*)(Kb + (db + u) * 32); kc[u] = *(const LAS bf16x8*)(Kb + 32 * 272 + (db + u) * 32); }
;         __builtin_amdgcn_sched_barrier(0);
; #pragma unroll
;         for (int u = 0; u < KBAT; ++u) { const int d0 = db + u; const bf16x8 qf = d0 < NQR ? qr[d0 < NQR ? d0 : 0] : qx[d0 >= NQR ? d0 - NQR : 0];
;           p0 = __builtin_amdgcn_mfma_f32_32x32x16_bf16(ka[u], qf, p0, 0, 0, 0);
;           p1 = __builtin_amdgcn_mfma_f32_32x32x16_bf16(kc[u], qf, p1, 0, 0, 0); }
;         __builtin_amdgcn_sched_barrier(0); }
;       if (pre) AT_WRITE_K(cur ^ 1);
.Lcq_w1:
	v_mfma_f32_32x32x16_bf16 v[146:161], v[210:213], v[206:209], v[146:161]
	v_mfma_f32_32x32x16_bf16 v[130:145], v[240:243], v[206:209], v[130:145]
	ds_read_b128 v[206:209], v221 offset:160
	ds_read_b128 v[210:213], v221 offset:8864
	s_waitcnt lgkmcnt(1)
	v_mfma_f32_32x32x16_bf16 v[146:161], v[206:209], v[202:205], v[146:161]
	s_waitcnt lgkmcnt(0)
	v_mfma_f32_32x32x16_bf16 v[130:145], v[210:213], v[202:205], v[130:145]
	ds_read_b128 v[202:205], v221 offset:192
	ds_read_b128 v[206:209], v221 offset:8896
	s_waitcnt lgkmcnt(1)
	v_mfma_f32_32x32x16_bf16 v[146:161], v[202:205], v[198:201], v[146:161]
	s_waitcnt lgkmcnt(0)
	v_mfma_f32_32x32x16_bf16 v[130:145], v[206:209], v[198:201], v[130:145]
	ds_read_b128 v[198:201], v221 offset:224
	ds_read_b128 v[202:205], v221 offset:8928
	s_waitcnt lgkmcnt(1)
	v_mfma_f32_32x32x16_bf16 v[146:161], v[198:201], v[194:197], v[146:161]
	s_waitcnt lgkmcnt(0)
	v_mfma_f32_32x32x16_bf16 v[130:145], v[202:205], v[194:197], v[130:145]
	s_and_b64 vcc, exec, s[2:3]
	s_cbranch_vccnz .LBB0_1424
	s_xor_b32 s20, s16, 1
	s_mulk_i32 s20, 0x4400
	v_add_u32_e32 v194, s20, v234
	s_waitcnt vmcnt(2)
	ds_write_b128 v194, v[178:181]
	ds_write_b128 v194, v[182:185] offset:128

; #define LAS __attribute__((address_space(3)))
; template <int MODE, int DV> ...
;     ...
;     if (act) {
;       const LAS unsigned char* Vb = lds + 34816 + cur * VBYTES + r32 * 136 + hi * 8;
; #pragma unroll
;       for (int dbb = 0; dbb < ND; dbb += VBAT) { bf16x8 vf[VBAT * 4];
; #pragma unroll
;         for (int u = 0; u < VBAT; ++u)
; #pragma unroll
;           for (int s = 0; s < 4; ++s) { const int d = dbb + u; const s16x4 lo4 = *(const LAS s16x4*)(Vb + d * 32 * 136 + s * 32), hi4 = *(const LAS s16x4*)(Vb + d * 32 * 136 + s * 32 + 16);
;             vf[u * 4 + s] = __builtin_shufflevector(lo4, hi4, 0, 1, 2, 3, 4, 5, 6, 7); }
;         __builtin_amdgcn_sched_barrier(0);
; #pragma unroll
;         for (int u = 0; u < VBAT; ++u)
; #pragma unroll
;           for (int s = 0; s < 4; ++s) o[dbb + u] = __builtin_amdgcn_mfma_f32_32x32x16_bf16(pa[s], vf[u * 4 + s], o[dbb + u], 0, 0, 0);
;         __builtin_amdgcn_sched_barrier(0); }
;     }
.LBB0_1435:
	s_mul_i32 s4, s16, 0x8800
	s_waitcnt lgkmcnt(0)
	v_add_u32_e32 v194, s4, v233
	v_add_u32_e32 v158, 0x8800, v194
	ds_read2_b64 v[146:149], v158 offset1:2
	ds_read2_b64 v[150:153], v158 offset0:4 offset1:6
	ds_read2_b64 v[154:157], v158 offset0:8 offset1:10
	ds_read2_b64 v[158:161], v158 offset0:12 offset1:14
	s_waitcnt lgkmcnt(3)
	v_mfma_f32_32x32x16_bf16 v[2:17], v[130:133], v[146:149], v[2:17]
	s_waitcnt lgkmcnt(2)
	v_mfma_f32_32x32x16_bf16 v[2:17], v[134:137], v[150:153], v[2:17]
	s_waitcnt lgkmcnt(1)
	v_mfma_f32_32x32x16_bf16 v[2:17], v[138:141], v[154:157], v[2:17]
	s_waitcnt lgkmcnt(0)
	v_mfma_f32_32x32x16_bf16 v[2:17], v[142:145], v[158:161], v[2:17]
	v_add_u32_e32 v158, 0x9800, v194
	ds_read2_b64 v[146:149], v158 offset0:32 offset1:34
	ds_read2_b64 v[150:153], v158 offset0:36 offset1:38
	ds_read2_b64 v[154:157], v158 offset0:40 offset1:42
	ds_read2_b64 v[158:161], v158 offset0:44 offset1:46
	s_waitcnt lgkmcnt(3)
	v_mfma_f32_32x32x16_bf16 v[114:129], v[130:133], v[146:149], v[114:129]
	s_waitcnt lgkmcnt(2)
	v_mfma_f32_32x32x16_bf16 v[114:129], v[134:137], v[150:153], v[114:129]
	s_waitcnt lgkmcnt(1)
	v_mfma_f32_32x32x16_bf16 v[114:129], v[138:141], v[154:157], v[114:129]
	s_waitcnt lgkmcnt(0)
	v_mfma_f32_32x32x16_bf16 v[114:129], v[142:145], v[158:161], v[114:129]
	v_add_u32_e32 v158, 0xa800, v194
	ds_read2_b64 v[146:149], v158 offset0:64 offset1:66
	ds_read2_b64 v[150:153], v158 offset0:68 offset1:70
	ds_read2_b64 v[154:157], v158 offset0:72 offset1:74
	ds_read2_b64 v[158:161], v158 offset0:76 offset1:78
	s_waitcnt lgkmcnt(3)
	v_mfma_f32_32x32x16_bf16 v[18:33], v[130:133], v[146:149], v[18:33]
	s_waitcnt lgkmcnt(2)
	v_mfma_f32_32x32x16_bf16 v[18:33], v[134:137], v[150:153], v[18:33]
	s_waitcnt lgkmcnt(1)
	v_mfma_f32_32x32x16_bf16 v[18:33], v[138:141], v[154:157], v[18:33]
	s_waitcnt lgkmcnt(0)
	v_mfma_f32_32x32x16_bf16 v[18:33], v[142:145], v[158:161], v[18:33]
	v_add_u32_e32 v158, 0xb800, v194
	ds_read2_b64 v[146:149], v158 offset0:96 offset1:98
	ds_read2_b64 v[150:153], v158 offset0:100 offset1:102
	ds_read2_b64 v[154:157], v158 offset0:104 offset1:106
	ds_read2_b64 v[158:161], v158 offset0:108 offset1:110
	s_waitcnt lgkmcnt(3)
	v_mfma_f32_32x32x16_bf16 v[34:49], v[130:133], v[146:149], v[34:49]
	s_waitcnt lgkmcnt(2)
	v_mfma_f32_32x32x16_bf16 v[34:49], v[134:137], v[150:153], v[34:49]
	s_waitcnt lgkmcnt(1)
	v_mfma_f32_32x32x16_bf16 v[34:49], v[138:141], v[154:157], v[34:49]
	s_waitcnt lgkmcnt(0)
	v_mfma_f32_32x32x16_bf16 v[34:49], v[142:145], v[158:161], v[34:49]
	v_add_u32_e32 v158, 0xc800, v194
	ds_read2_b64 v[146:149], v158 offset0:128 offset1:130
	ds_read2_b64 v[150:153], v158 offset0:132 offset1:134
	ds_read2_b64 v[154:157], v158 offset0:136 offset1:138
	ds_read2_b64 v[158:161], v158 offset0:140 offset1:142
	s_waitcnt lgkmcnt(3)
	v_mfma_f32_32x32x16_bf16 v[50:65], v[130:133], v[146:149], v[50:65]
	s_waitcnt lgkmcnt(2)
	v_mfma_f32_32x32x16_bf16 v[50:65], v[134:137], v[150:153], v[50:65]
	s_waitcnt lgkmcnt(1)
	v_mfma_f32_32x32x16_bf16 v[50:65], v[138:141], v[154:157], v[50:65]
	s_waitcnt lgkmcnt(0)
	v_mfma_f32_32x32x16_bf16 v[50:65], v[142:145], v[158:161], v[50:65]
	v_add_u32_e32 v158, 0xd800, v194
	ds_read2_b64 v[146:149], v158 offset0:160 offset1:162
	ds_read2_b64 v[150:153], v158 offset0:164 offset1:166
	ds_read2_b64 v[154:157], v158 offset0:168 offset1:170
	ds_read2_b64 v[158:161], v158 offset0:172 offset1:174
	s_waitcnt lgkmcnt(3)
	v_mfma_f32_32x32x16_bf16 v[66:81], v[130:133], v[146:149], v[66:81]
	s_waitcnt lgkmcnt(2)
	v_mfma_f32_32x32x16_bf16 v[66:81], v[134:137], v[150:153], v[66:81]
	s_waitcnt lgkmcnt(1)
	v_mfma_f32_32x32x16_bf16 v[66:81], v[138:141], v[154:157], v[66:81]
	s_waitcnt lgkmcnt(0)
	v_mfma_f32_32x32x16_bf16 v[66:81], v[142:145], v[158:161], v[66:81]
	v_add_u32_e32 v158, 0xe800, v194
	ds_read2_b64 v[146:149], v158 offset0:192 offset1:194
	ds_read2_b64 v[150:153], v158 offset0:196 offset1:198
	ds_read2_b64 v[154:157], v158 offset0:200 offset1:202
	ds_read2_b64 v[158:161], v158 offset0:204 offset1:206
	s_waitcnt lgkmcnt(3)
	v_mfma_f32_32x32x16_bf16 v[82:97], v[130:133], v[146:149], v[82:97]
	s_waitcnt lgkmcnt(2)
	v_mfma_f32_32x32x16_bf16 v[82:97], v[134:137], v[150:153], v[82:97]
	s_waitcnt lgkmcnt(1)
	v_mfma_f32_32x32x16_bf16 v[82:97], v[138:141], v[154:157], v[82:97]
	s_waitcnt lgkmcnt(0)
	v_mfma_f32_32x32x16_bf16 v[82:97], v[142:145], v[158:161], v[82:97]
	v_add_u32_e32 v158, 0xf800, v194
	ds_read2_b64 v[146:149], v158 offset0:224 offset1:226
	ds_read2_b64 v[150:153], v158 offset0:228 offset1:230
	ds_read2_b64 v[154:157], v158 offset0:232 offset1:234
	ds_read2_b64 v[158:161], v158 offset0:236 offset1:238
	s_waitcnt lgkmcnt(3)
	v_mfma_f32_32x32x16_bf16 v[98:113], v[130:133], v[146:149], v[98:113]
	s_waitcnt lgkmcnt(2)
	v_mfma_f32_32x32x16_bf16 v[98:113], v[134:137], v[150:153], v[98:113]
	s_waitcnt lgkmcnt(1)
	v_mfma_f32_32x32x16_bf16 v[98:113], v[138:141], v[154:157], v[98:113]
	s_waitcnt lgkmcnt(0)
	v_mfma_f32_32x32x16_bf16 v[98:113], v[142:145], v[158:161], v[98:113]

; DI unsigned cvtpk(float lo, float hi) { unsigned r; asm volatile("v_cvt_pk_bf16_f32 %0, %1, %2" : "=v"(r) : "v"(lo), "v"(hi)); return r; }
; DI float bf2f(bf16_t b) { return __uint_as_float(((unsigned)b) << 16); }
; DI float wsum(float v) { for (int o = 32; o; o >>= 1) v += __shfl_xor(v, o); return v; }
; __global__ void __launch_bounds__(NTHR) fwd_megakernel(Params p) {
;     ...
;     { PHASE_VARS const bf16_t* oc = (const bf16_t*)(ws + O_OC); bf16_t* yc = (bf16_t*)(ws + O_YC);
;       const float lamv = scal[l * 2], omli = scal[l * 2 + 1];
;       for (int it = gw; it < T * 4; it += nw) {
;         const int row = it >> 2, head = it & 3;
;         const s16x4 a = __builtin_nontemporal_load((const s16x4*)(oc + (size_t)row * 2048 + head * 512 + lane * 4)), b4 = __builtin_nontemporal_load((const s16x4*)(oc + (size_t)row * 2048 + head * 512 + 256 + lane * 4));
;         float v[4], s = 0; for (int j = 0; j < 4; ++j) { v[j] = bf2f((bf16_t)a[j]) - lamv * bf2f((bf16_t)b4[j]); s += v[j] * v[j]; }
;         const float rs = rsqrtf(wsum(s) * (1.f / 256.f) + 1e-6f);
;         const f32x4 gg = *(const f32x4*)(p.subln_g + l * 256 + lane * 4);
;         float o4[4]; for (int j = 0; j < 4; ++j) o4[j] = v[j] * rs * gg[j] * omli;
;         *(u32x2*)(yc + (size_t)row * 1024 + head * 256 + lane * 4) = (u32x2){cvtpk(o4[0], o4[1]), cvtpk(o4[2], o4[3])};
;       }
;     }
.LBB0_1604:
	s_or_b64 exec, exec, s[0:1]
	v_mov_b32_e32 v3, v248
	s_mov_b32 s0, s85
	s_mov_b32 s7, s73
	v_ashrrev_i32_e32 v0, 6, v3
	v_lshl_add_u32 v10, s0, 3, v0
	v_readlane_b32 s0, v252, 41
	v_readlane_b32 s1, v252, 42
	s_mov_b32 s1, s73
	s_mov_b64 s[58:59], s[0:1]
	s_or_b32 s6, s0, 1
	s_mov_b32 s0, 0x8000
	v_cmp_gt_i32_e32 vcc, s0, v10
	s_and_saveexec_b64 s[0:1], vcc
	v_readlane_b32 s24, v252, 30
	v_readlane_b32 s25, v252, 31
	s_mov_b32 s25, 0x800000
	s_cbranch_execz .LBB0_1607
	s_lshl_b64 s[2:3], s[6:7], 2
	v_readlane_b32 s4, v249, 18
	v_readlane_b32 s5, v249, 19
	s_add_u32 s2, s4, s2
	s_addc_u32 s3, s5, s3
	global_load_dword v11, v1, s[2:3]
	s_lshl_b64 s[2:3], s[58:59], 2
	s_add_u32 s2, s4, s2
	s_addc_u32 s3, s5, s3
	global_load_dword v2, v1, s[2:3]
	v_lshlrev_b32_e32 v0, 2, v3
	v_and_b32_e32 v18, 0xfc, v0
	v_and_b32_e32 v0, 64, v229
	v_add_u32_e32 v0, 64, v0
	v_xor_b32_e32 v4, 32, v229
	v_cmp_lt_i32_e32 vcc, v4, v0
	v_readlane_b32 s2, v252, 29
	s_lshl_b32 s72, s2, 8
	v_cndmask_b32_e32 v4, v229, v4, vcc
	v_lshlrev_b32_e32 v12, 2, v4
	v_xor_b32_e32 v4, 16, v229
	v_cmp_lt_i32_e32 vcc, v4, v0
	v_readlane_b32 s8, v249, 0
	s_lshl_b64 s[2:3], s[72:73], 2
	v_cndmask_b32_e32 v4, v229, v4, vcc
	v_lshlrev_b32_e32 v13, 2, v4
	v_xor_b32_e32 v4, 8, v229
	v_cmp_lt_i32_e32 vcc, v4, v0
	v_readlane_b32 s14, v249, 6
	v_readlane_b32 s15, v249, 7
	v_cndmask_b32_e32 v4, v229, v4, vcc
	v_lshlrev_b32_e32 v14, 2, v4
	v_xor_b32_e32 v4, 4, v229
	v_cmp_lt_i32_e32 vcc, v4, v0
	s_add_u32 s2, s14, s2
	s_addc_u32 s3, s15, s3
	v_cndmask_b32_e32 v4, v229, v4, vcc
	v_lshlrev_b32_e32 v15, 2, v4
	v_xor_b32_e32 v4, 2, v229
	v_cmp_lt_i32_e32 vcc, v4, v0
	v_bfe_u32 v3, v3, 6, 2
	v_lshlrev_b32_e32 v6, 10, v3
	v_cndmask_b32_e32 v4, v229, v4, vcc
	v_lshlrev_b32_e32 v16, 2, v4
	v_xor_b32_e32 v4, 1, v229
	v_cmp_lt_i32_e32 vcc, v4, v0
	v_mov_b32_e32 v7, v1
	v_readlane_b32 s9, v249, 1
	v_cndmask_b32_e32 v0, v229, v4, vcc
	v_lshlrev_b32_e32 v17, 2, v0
	v_lshlrev_b32_e32 v0, 2, v18
	v_lshl_add_u64 v[4:5], s[2:3], 0, v[0:1]
	v_readlane_b32 s2, v251, 20
	v_readlane_b32 s3, v251, 21
	v_lshlrev_b32_e32 v0, 9, v3
	v_readlane_b32 s10, v249, 2
	v_lshl_add_u64 v[8:9], s[2:3], 0, v[6:7]
	v_readlane_b32 s2, v251, 24
	v_readlane_b32 s3, v251, 25
	v_readlane_b32 s11, v249, 3
	v_readlane_b32 s12, v249, 4
	v_lshl_add_u64 v[6:7], s[2:3], 0, v[0:1]
	v_lshlrev_b32_e32 v0, 1, v18
	v_lshl_add_u64 v[6:7], v[6:7], 0, v[0:1]
	v_lshl_add_u64 v[8:9], v[8:9], 0, v[0:1]
	s_mov_b64 s[2:3], 0
	v_readlane_b32 s13, v249, 5
	v_readlane_b32 s16, v249, 8
	v_readlane_b32 s17, v249, 9
	v_readlane_b32 s18, v249, 10
	v_readlane_b32 s19, v249, 11
	v_readlane_b32 s20, v249, 12
	v_readlane_b32 s21, v249, 13
	v_readlane_b32 s22, v249, 14
	v_readlane_b32 s23, v249, 15
	s_waitcnt vmcnt(0)
	v_mov_b32_e32 v3, v2
	global_load_dwordx4 v[40:43], v[4:5], off
	s_waitcnt vmcnt(0)
.LBB0_1606:
	v_ashrrev_i32_e32 v22, 2, v10
	v_ashrrev_i32_e32 v23, 31, v22
	v_lshlrev_b64 v[18:19], 12, v[22:23]
	v_lshl_add_u64 v[18:19], v[8:9], 0, v[18:19]
	global_load_dwordx2 v[20:21], v[18:19], off nt
	s_nop 0
	global_load_dwordx2 v[18:19], v[18:19], off offset:512 nt
	v_add_u32_e32 v10, s24, v10
	s_movk_i32 s4, 0x7fff
	s_waitcnt vmcnt(1)
	v_and_b32_e32 v25, 0xffff0000, v20
	v_lshlrev_b32_e32 v24, 16, v20
	s_waitcnt vmcnt(0)
	v_and_b32_e32 v27, 0xffff0000, v18
	v_lshlrev_b32_e32 v26, 16, v18
	v_pk_fma_f32 v[24:25], v[2:3], v[26:27], v[24:25] neg_lo:[1,0,0] neg_hi:[1,0,0]
	v_and_b32_e32 v29, 0xffff0000, v21
	v_lshlrev_b32_e32 v28, 16, v21
	v_and_b32_e32 v21, 0xffff0000, v19
	v_lshlrev_b32_e32 v20, 16, v19
	v_pk_mul_f32 v[26:27], v[24:25], v[24:25]
	v_pk_fma_f32 v[28:29], v[2:3], v[20:21], v[28:29] neg_lo:[1,0,0] neg_hi:[1,0,0]
	v_add_f32_e32 v0, v26, v27
	v_pk_mul_f32 v[18:19], v[28:29], v[28:29]
	s_nop 0
	v_add_f32_e32 v0, v0, v18
	v_add_f32_e32 v0, v0, v19
	ds_bpermute_b32 v18, v12, v0
	s_waitcnt lgkmcnt(0)
	v_add_f32_e32 v0, v0, v18
	ds_bpermute_b32 v18, v13, v0
	s_waitcnt lgkmcnt(0)
	v_add_f32_e32 v0, v0, v18
	ds_bpermute_b32 v18, v14, v0
	s_waitcnt lgkmcnt(0)
	v_add_f32_e32 v0, v0, v18
	ds_bpermute_b32 v18, v15, v0
	s_waitcnt lgkmcnt(0)
	v_add_f32_e32 v0, v0, v18
	ds_bpermute_b32 v18, v16, v0
	s_waitcnt lgkmcnt(0)
	v_add_f32_e32 v0, v0, v18
	ds_bpermute_b32 v18, v17, v0
	s_waitcnt lgkmcnt(0)
	v_add_f32_e32 v0, v0, v18
	v_fmamk_f32 v0, v0, 0x3b800000, v212
	v_cmp_gt_f32_e32 vcc, s25, v0
	v_mul_f32_e32 v18, 0x4b800000, v0
	s_nop 0
	v_cndmask_b32_e32 v0, v0, v18, vcc
	v_rsq_f32_e32 v0, v0
	s_nop 0
	v_mul_f32_e32 v18, 0x45800000, v0
	v_cndmask_b32_e32 v0, v0, v18, vcc
	v_mul_f32_e32 v24, v0, v24
	v_cmp_lt_i32_e32 vcc, s4, v10
	s_or_b64 s[2:3], vcc, s[2:3]
	v_mul_f32_e32 v18, v40, v24
	v_mul_f32_e32 v24, v0, v25
	v_mul_f32_e32 v19, v41, v24
	v_mul_f32_e32 v24, v0, v28
	v_mul_f32_e32 v20, v42, v24
	v_mul_f32_e32 v0, v0, v29
	v_mul_f32_e32 v18, v11, v18
	v_mul_f32_e32 v19, v11, v19
	v_mul_f32_e32 v20, v11, v20
	v_mul_f32_e32 v0, v43, v0
	v_mul_f32_e32 v0, v11, v0
	v_cvt_pk_bf16_f32 v18, v18, v19
	v_cvt_pk_bf16_f32 v19, v20, v0
	v_lshlrev_b64 v[20:21], 11, v[22:23]
	v_lshl_add_u64 v[20:21], v[6:7], 0, v[20:21]
	global_store_dwordx2 v[20:21], v[18:19], off
	s_andn2_b64 exec, exec, s[2:3]
	s_cbranch_execnz .LBB0_1606

;   DI void fused(AccT& acc, const Unit& u, LAS unsigned char* lds, int tid, int wr, int wc, int fr, int fq) const {
;     ...
;     const int row0 = u.pm * BM + wr * 64 + fr, col0 = u.pn * BM + wc * 32 + 4 * fq, b = (u.pm * BM) >> 12;
;     { f32x4 g[2][2], xc[2][2], xn[2][2];
; #pragma unroll
;       for (int bj = 0; bj < 2; ++bj)
; #pragma unroll
;         for (int n = 0; n < 2; ++n) g[bj][n] = *(const f32x4*)(gv + b * 12288 + col0 + bj * HALF + n * 16);
;       { const float* xr = xin + (size_t)row0 * DM + col0;
; #pragma unroll
;         for (int bj = 0; bj < 2; ++bj)
; #pragma unroll
;           for (int n = 0; n < 2; ++n) xc[bj][n] = __builtin_nontemporal_load((const f32x4*)(xr + bj * HALF + n * 16)); }
; #pragma unroll
;       for (int k = 0; k < 8; ++k) { const int ai = k >> 2, m = k & 3;
;         if (k < 7) { const int k1 = k + 1; const float* xr = xin + (size_t)(row0 + (k1 >> 2) * HALF + (k1 & 3) * 16) * DM + col0; asm volatile("" : "+v"(xr));
; #pragma unroll
;           for (int bj = 0; bj < 2; ++bj)
; #pragma unroll
;             for (int n = 0; n < 2; ++n) xn[bj][n] = __builtin_nontemporal_load((const f32x4*)(xr + bj * HALF + n * 16)); }
; #pragma unroll
;         for (int bj = 0; bj < 2; ++bj)
; #pragma unroll
;           for (int n = 0; n < 2; ++n)
; #pragma unroll
;             for (int j = 0; j < 4; ++j) acc[ai][bj][m][n][j] = ALPHA * xc[bj][n][j] + g[bj][n][j] * acc[ai][bj][m][n][j];
;         asm volatile("" :: "v"(acc[ai][0][m][0]), "v"(acc[ai][0][m][1]), "v"(acc[ai][1][m][0]), "v"(acc[ai][1][m][1]));
; #pragma unroll
;         for (int bj = 0; bj < 2; ++bj)
; #pragma unroll
;           for (int n = 0; n < 2; ++n) xc[bj][n] = xn[bj][n]; } }
.LBB0_1785:
	v_readlane_b32 s0, v252, 34
	s_lshl_b32 s2, s9, 5
	v_readlane_b32 s1, v252, 35
	v_readlane_b32 s40, v249, 53
	s_and_b64 s[0:1], s[0:1], exec
	v_readlane_b32 s41, v249, 54
	s_mov_b64 s[4:5], s[40:41]
	v_readlane_b32 s0, v250, 9
	s_cselect_b32 s1, s5, s0
	v_readlane_b32 s0, v250, 8
	s_cselect_b32 s0, s4, s0
	s_lshl_b32 s3, s10, 8
	s_or_b32 s2, s3, s2
	v_lshl_or_b32 v178, v167, 2, s2
	s_lshr_b32 s2, s8, 4
	s_mulk_i32 s2, 0x3000
	s_lshl_b32 s22, s8, 8
	s_ashr_i32 s3, s2, 31
	s_add_i32 s4, s22, s38
	s_lshl_b64 s[12:13], s[2:3], 2
	s_add_u32 s2, s26, s12
	v_ashrrev_i32_e32 v179, 31, v178
	s_addc_u32 s3, s27, s13
	v_lshlrev_b64 v[180:181], 2, v[178:179]
	v_lshl_add_u64 v[122:123], s[2:3], 0, v[180:181]
	v_lshl_add_u64 v[124:125], v[122:123], 0, s[76:77]
	v_add_co_u32_e32 v122, vcc, s82, v122
	v_or_b32_e32 v164, s4, v204
	s_nop 0
	v_addc_co_u32_e32 v123, vcc, 0, v123, vcc
	v_ashrrev_i32_e32 v165, 31, v164
	s_barrier
	global_load_dwordx4 v[138:141], v[122:123], off
	global_load_dwordx4 v[150:153], v[124:125], off offset:64
	global_load_dwordx4 v[146:149], v[124:125], off offset:512
	global_load_dwordx4 v[142:145], v[124:125], off offset:576
	v_lshlrev_b64 v[122:123], 13, v[164:165]
	v_lshl_add_u64 v[122:123], s[0:1], 0, v[122:123]
	v_lshl_add_u64 v[162:163], v[122:123], 0, v[180:181]
	global_load_dwordx4 v[122:125], v[162:163], off nt
	global_load_dwordx4 v[126:129], v[162:163], off offset:64 nt
	global_load_dwordx4 v[154:157], v[162:163], off offset:512 nt
	global_load_dwordx4 v[158:161], v[162:163], off offset:576 nt
	v_or_b32_e32 v168, 16, v164
	v_ashrrev_i32_e32 v169, 31, v168
	v_lshlrev_b64 v[168:169], 13, v[168:169]
	v_lshl_add_u64 v[168:169], s[0:1], 0, v[168:169]
	v_lshl_add_u64 v[176:177], v[168:169], 0, v[180:181]
	global_load_dwordx4 v[168:171], v[176:177], off nt
	global_load_dwordx4 v[172:175], v[176:177], off offset:64 nt
	global_load_dwordx4 v[182:185], v[176:177], off offset:512 nt
	global_load_dwordx4 v[186:189], v[176:177], off offset:576 nt
	s_mov_b32 s2, 0x3fb504f3
	v_xor_b32_e32 v0, 16, v229
	v_readlane_b32 s42, v249, 55
	v_readlane_b32 s43, v249, 56
	v_readlane_b32 s44, v249, 57
	v_readlane_b32 s45, v249, 58
	v_readlane_b32 s46, v249, 59
	v_readlane_b32 s47, v249, 60
	v_readlane_b32 s48, v249, 61
	v_readlane_b32 s49, v249, 62
	v_readlane_b32 s50, v249, 63
	v_readlane_b32 s51, v250, 0
	v_readlane_b32 s52, v250, 1
	v_readlane_b32 s53, v250, 2
	v_readlane_b32 s54, v250, 3
	v_readlane_b32 s55, v250, 4
	s_waitcnt vmcnt(4)
	v_pk_mul_f32 v[110:111], v[110:111], v[138:139]
	v_pk_mul_f32 v[112:113], v[112:113], v[140:141]
	v_pk_mul_f32 v[102:103], v[102:103], v[146:147]
	v_pk_mul_f32 v[108:109], v[108:109], v[152:153]
	v_pk_fma_f32 v[110:111], v[122:123], s[2:3], v[110:111] op_sel_hi:[1,0,1]
	v_or_b32_e32 v122, 32, v164
	v_ashrrev_i32_e32 v123, 31, v122
	v_lshlrev_b64 v[122:123], 13, v[122:123]
	v_lshl_add_u64 v[122:123], s[0:1], 0, v[122:123]
	v_pk_mul_f32 v[106:107], v[106:107], v[150:151]
	v_pk_mul_f32 v[104:105], v[104:105], v[148:149]
	v_pk_fma_f32 v[102:103], v[154:155], s[2:3], v[102:103] op_sel_hi:[1,0,1]
	v_pk_mul_f32 v[4:5], v[4:5], v[144:145]
	v_pk_mul_f32 v[2:3], v[2:3], v[142:143]
	v_lshl_add_u64 v[154:155], v[122:123], 0, v[180:181]
	v_pk_fma_f32 v[112:113], v[124:125], s[2:3], v[112:113] op_sel_hi:[1,0,1]
	v_pk_fma_f32 v[106:107], v[126:127], s[2:3], v[106:107] op_sel_hi:[1,0,1]
	v_pk_fma_f32 v[108:109], v[128:129], s[2:3], v[108:109] op_sel_hi:[1,0,1]
	v_pk_fma_f32 v[104:105], v[156:157], s[2:3], v[104:105] op_sel_hi:[1,0,1]
	v_pk_fma_f32 v[2:3], v[158:159], s[2:3], v[2:3] op_sel_hi:[1,0,1]
	v_pk_fma_f32 v[4:5], v[160:161], s[2:3], v[4:5] op_sel_hi:[1,0,1]
	v_or_b32_e32 v164, 48, v164
	global_load_dwordx4 v[126:129], v[154:155], off nt
	global_load_dwordx4 v[122:125], v[154:155], off offset:64 nt
	global_load_dwordx4 v[158:161], v[154:155], off offset:512 nt
	s_nop 0
	global_load_dwordx4 v[154:157], v[154:155], off offset:576 nt
	v_ashrrev_i32_e32 v165, 31, v164
	v_lshlrev_b64 v[164:165], 13, v[164:165]
	v_lshl_add_u64 v[164:165], s[0:1], 0, v[164:165]
	v_pk_mul_f32 v[100:101], v[100:101], v[140:141]
	v_pk_mul_f32 v[98:99], v[98:99], v[138:139]
	v_pk_mul_f32 v[96:97], v[96:97], v[152:153]
	v_pk_mul_f32 v[94:95], v[94:95], v[150:151]
	v_pk_mul_f32 v[92:93], v[92:93], v[148:149]
	v_pk_mul_f32 v[90:91], v[90:91], v[146:147]
	v_pk_mul_f32 v[88:89], v[88:89], v[144:145]
	v_pk_mul_f32 v[86:87], v[86:87], v[142:143]
	v_lshl_add_u64 v[164:165], v[164:165], 0, v[180:181]
	s_waitcnt vmcnt(4) lgkmcnt(0)
;   DI void fused(AccT& acc, const Unit& u, LAS unsigned char* lds, int tid, int wr, int wc, int fr, int fq) const {
;     ...
;       for (int k = 0; k < 8; ++k) { const int ai = k >> 2, m = k & 3;
;         if (k < 7) { const int k1 = k + 1; const float* xr = xin + (size_t)(row0 + (k1 >> 2) * HALF + (k1 & 3) * 16) * DM + col0; asm volatile("" : "+v"(xr));
; #pragma unroll
;           for (int bj = 0; bj < 2; ++bj)
; #pragma unroll
;             for (int n = 0; n < 2; ++n) xn[bj][n] = __builtin_nontemporal_load((const f32x4*)(xr + bj * HALF + n * 16)); }
; #pragma unroll
;         for (int bj = 0; bj < 2; ++bj)
; #pragma unroll
;           for (int n = 0; n < 2; ++n)
; #pragma unroll
;             for (int j = 0; j < 4; ++j) acc[ai][bj][m][n][j] = ALPHA * xc[bj][n][j] + g[bj][n][j] * acc[ai][bj][m][n][j];
;         asm volatile("" :: "v"(acc[ai][0][m][0]), "v"(acc[ai][0][m][1]), "v"(acc[ai][1][m][0]), "v"(acc[ai][1][m][1]));
; #pragma unroll
;         for (int bj = 0; bj < 2; ++bj)
; #pragma unroll
;           for (int n = 0; n < 2; ++n) xc[bj][n] = xn[bj][n]; } }
	v_pk_fma_f32 v[98:99], v[168:169], s[2:3], v[98:99] op_sel_hi:[1,0,1]
	v_pk_fma_f32 v[100:101], v[170:171], s[2:3], v[100:101] op_sel_hi:[1,0,1]
	v_pk_fma_f32 v[94:95], v[172:173], s[2:3], v[94:95] op_sel_hi:[1,0,1]
	v_pk_fma_f32 v[96:97], v[174:175], s[2:3], v[96:97] op_sel_hi:[1,0,1]
	v_pk_fma_f32 v[90:91], v[182:183], s[2:3], v[90:91] op_sel_hi:[1,0,1]
	v_pk_fma_f32 v[92:93], v[184:185], s[2:3], v[92:93] op_sel_hi:[1,0,1]
	v_pk_fma_f32 v[86:87], v[186:187], s[2:3], v[86:87] op_sel_hi:[1,0,1]
	v_pk_fma_f32 v[88:89], v[188:189], s[2:3], v[88:89] op_sel_hi:[1,0,1]
	v_pk_mul_f32 v[114:115], v[114:115], v[150:151]
	global_load_dwordx4 v[168:171], v[164:165], off nt
	global_load_dwordx4 v[172:175], v[164:165], off offset:64 nt
	global_load_dwordx4 v[182:185], v[164:165], off offset:512 nt
	global_load_dwordx4 v[186:189], v[164:165], off offset:576 nt
	v_pk_mul_f32 v[78:79], v[78:79], v[142:143]
	s_mov_b64 s[0:1], 0x100000
	v_pk_mul_f32 v[120:121], v[120:121], v[140:141]
	v_pk_mul_f32 v[118:119], v[118:119], v[138:139]
	v_pk_mul_f32 v[116:117], v[116:117], v[152:153]
	v_pk_mul_f32 v[84:85], v[84:85], v[148:149]
	v_pk_mul_f32 v[82:83], v[82:83], v[146:147]
	v_pk_mul_f32 v[80:81], v[80:81], v[144:145]
	v_pk_mul_f32 v[48:49], v[48:49], v[140:141]
	v_pk_mul_f32 v[46:47], v[46:47], v[138:139]
	v_pk_mul_f32 v[36:37], v[36:37], v[152:153]
	v_pk_mul_f32 v[34:35], v[34:35], v[150:151]
	v_pk_mul_f32 v[28:29], v[28:29], v[148:149]
	v_pk_mul_f32 v[26:27], v[26:27], v[146:147]
	v_pk_mul_f32 v[24:25], v[24:25], v[144:145]
	v_pk_mul_f32 v[22:23], v[22:23], v[142:143]
	v_pk_mul_f32 v[70:71], v[70:71], v[150:151]
	v_pk_mul_f32 v[54:55], v[54:55], v[142:143]
	v_pk_mul_f32 v[76:77], v[76:77], v[140:141]
	v_pk_mul_f32 v[74:75], v[74:75], v[138:139]
	v_pk_mul_f32 v[72:73], v[72:73], v[152:153]
	v_pk_mul_f32 v[60:61], v[60:61], v[148:149]
	v_pk_mul_f32 v[58:59], v[58:59], v[146:147]
	v_pk_mul_f32 v[56:57], v[56:57], v[144:145]
	v_pk_mul_f32 v[30:31], v[30:31], v[142:143]
	v_pk_mul_f32 v[40:41], v[40:41], v[148:149]
	v_pk_mul_f32 v[38:39], v[38:39], v[146:147]
	v_pk_mul_f32 v[32:33], v[32:33], v[144:145]
	v_pk_mul_f32 v[14:15], v[14:15], v[142:143]
	v_pk_mul_f32 v[20:21], v[20:21], v[148:149]
	v_pk_mul_f32 v[16:17], v[16:17], v[144:145]
	v_pk_mul_f32 v[18:19], v[18:19], v[146:147]
	v_pk_mul_f32 v[12:13], v[12:13], v[148:149]
	v_pk_mul_f32 v[10:11], v[10:11], v[146:147]
	v_pk_mul_f32 v[8:9], v[8:9], v[144:145]
	v_pk_mul_f32 v[6:7], v[6:7], v[142:143]
	s_waitcnt vmcnt(4)
	v_pk_fma_f32 v[126:127], v[126:127], s[2:3], v[118:119] op_sel_hi:[1,0,1]
	v_pk_fma_f32 v[122:123], v[122:123], s[2:3], v[114:115] op_sel_hi:[1,0,1]
	v_pk_fma_f32 v[128:129], v[128:129], s[2:3], v[120:121] op_sel_hi:[1,0,1]
	v_pk_fma_f32 v[114:115], v[154:155], s[2:3], v[78:79] op_sel_hi:[1,0,1]
	v_lshl_add_u64 v[154:155], v[162:163], 0, s[0:1]
	v_pk_fma_f32 v[124:125], v[124:125], s[2:3], v[116:117] op_sel_hi:[1,0,1]
	v_pk_fma_f32 v[118:119], v[158:159], s[2:3], v[82:83] op_sel_hi:[1,0,1]
	v_pk_fma_f32 v[120:121], v[160:161], s[2:3], v[84:85] op_sel_hi:[1,0,1]
	v_pk_fma_f32 v[116:117], v[156:157], s[2:3], v[80:81] op_sel_hi:[1,0,1]
	s_mov_b64 s[0:1], 0x120000
	global_load_dwordx4 v[82:85], v[154:155], off nt
	global_load_dwordx4 v[78:81], v[154:155], off offset:64 nt
	global_load_dwordx4 v[158:161], v[154:155], off offset:512 nt
	s_nop 0
	global_load_dwordx4 v[154:157], v[154:155], off offset:576 nt
	v_lshl_add_u64 v[164:165], v[162:163], 0, s[0:1]
	s_mov_b64 s[0:1], 0x140000
	s_waitcnt vmcnt(4) lgkmcnt(0)
	v_pk_fma_f32 v[46:47], v[168:169], s[2:3], v[46:47] op_sel_hi:[1,0,1]
	v_pk_fma_f32 v[48:49], v[170:171], s[2:3], v[48:49] op_sel_hi:[1,0,1]
	v_pk_fma_f32 v[34:35], v[172:173], s[2:3], v[34:35] op_sel_hi:[1,0,1]
	v_pk_fma_f32 v[36:37], v[174:175], s[2:3], v[36:37] op_sel_hi:[1,0,1]
	v_pk_fma_f32 v[26:27], v[182:183], s[2:3], v[26:27] op_sel_hi:[1,0,1]
	v_pk_fma_f32 v[28:29], v[184:185], s[2:3], v[28:29] op_sel_hi:[1,0,1]
	v_pk_fma_f32 v[22:23], v[186:187], s[2:3], v[22:23] op_sel_hi:[1,0,1]
	v_pk_fma_f32 v[24:25], v[188:189], s[2:3], v[24:25] op_sel_hi:[1,0,1]
	s_waitcnt vmcnt(0)
	v_pk_fma_f32 v[82:83], v[82:83], s[2:3], v[74:75] op_sel_hi:[1,0,1]
	global_load_dwordx4 v[168:171], v[164:165], off nt
	global_load_dwordx4 v[172:175], v[164:165], off offset:64 nt
	global_load_dwordx4 v[182:185], v[164:165], off offset:512 nt
	global_load_dwordx4 v[186:189], v[164:165], off offset:576 nt
	v_pk_fma_f32 v[78:79], v[78:79], s[2:3], v[70:71] op_sel_hi:[1,0,1]
	v_pk_fma_f32 v[70:71], v[154:155], s[2:3], v[54:55] op_sel_hi:[1,0,1]
	v_lshl_add_u64 v[54:55], v[162:163], 0, s[0:1]
	v_pk_fma_f32 v[84:85], v[84:85], s[2:3], v[76:77] op_sel_hi:[1,0,1]
	v_pk_fma_f32 v[80:81], v[80:81], s[2:3], v[72:73] op_sel_hi:[1,0,1]
	v_pk_fma_f32 v[74:75], v[158:159], s[2:3], v[58:59] op_sel_hi:[1,0,1]
	v_pk_fma_f32 v[76:77], v[160:161], s[2:3], v[60:61] op_sel_hi:[1,0,1]
	v_pk_fma_f32 v[72:73], v[156:157], s[2:3], v[56:57] op_sel_hi:[1,0,1]
	v_pk_mul_f32 v[56:57], v[66:67], v[138:139]
	global_load_dwordx4 v[154:157], v[54:55], off nt
	global_load_dwordx4 v[158:161], v[54:55], off offset:64 nt
	global_load_dwordx4 v[190:193], v[54:55], off offset:512 nt
	global_load_dwordx4 v[194:197], v[54:55], off offset:576 nt
	v_pk_mul_f32 v[54:55], v[68:69], v[140:141]
	s_mov_b64 s[0:1], 0x160000
	s_waitcnt vmcnt(0) lgkmcnt(0)
; #define LAS __attribute__((address_space(3)))
; DI void ln_exchange(const AccT& acc, LAS float* red, float* stats, unsigned* cnt, int pm, int pn, int tid, int wr, int wc, int fr, int fq) {
; #pragma unroll
;   for (int ai = 0; ai < 2; ++ai)
; #pragma unroll
;     for (int m = 0; m < 4; ++m) {
;       float s1 = 0.f, s2 = 0.f;
; #pragma unroll
;       for (int bj = 0; bj < 2; ++bj)
; #pragma unroll
;         for (int n = 0; n < 2; ++n)
; #pragma unroll
;           for (int j = 0; j < 4; ++j) { const float x = acc[ai][bj][m][n][j]; s1 += x; s2 += x * x; }
;       s1 += __shfl_xor(s1, 16); s2 += __shfl_xor(s2, 16); s1 += __shfl_xor(s1, 32); s2 += __shfl_xor(s2, 32);
;       if (fq == 0) { const int rl = ai * 128 + wr * 64 + m * 16 + fr; red[(rl * 4 + wc) * 2] = s1; red[(rl * 4 + wc) * 2 + 1] = s2; }
;   DI void fused(AccT& acc, const Unit& u, LAS unsigned char* lds, int tid, int wr, int wc, int fr, int fq) const {
;     ...
;       for (int k = 0; k < 8; ++k) { const int ai = k >> 2, m = k & 3;
;         if (k < 7) { const int k1 = k + 1; const float* xr = xin + (size_t)(row0 + (k1 >> 2) * HALF + (k1 & 3) * 16) * DM + col0; asm volatile("" : "+v"(xr));
; #pragma unroll
;           for (int bj = 0; bj < 2; ++bj)
; #pragma unroll
;             for (int n = 0; n < 2; ++n) xn[bj][n] = __builtin_nontemporal_load((const f32x4*)(xr + bj * HALF + n * 16)); }
; #pragma unroll
;         for (int bj = 0; bj < 2; ++bj)
; #pragma unroll
;           for (int n = 0; n < 2; ++n)
; #pragma unroll
;             for (int j = 0; j < 4; ++j) acc[ai][bj][m][n][j] = ALPHA * xc[bj][n][j] + g[bj][n][j] * acc[ai][bj][m][n][j];
;         asm volatile("" :: "v"(acc[ai][0][m][0]), "v"(acc[ai][0][m][1]), "v"(acc[ai][1][m][0]), "v"(acc[ai][1][m][1]));
; #pragma unroll
;         for (int bj = 0; bj < 2; ++bj)
; #pragma unroll
;           for (int n = 0; n < 2; ++n) xc[bj][n] = xn[bj][n]; } }
	v_pk_fma_f32 v[68:69], v[170:171], s[2:3], v[54:55] op_sel_hi:[1,0,1]
	v_pk_mul_f32 v[54:55], v[64:65], v[152:153]
	v_pk_fma_f32 v[66:67], v[168:169], s[2:3], v[56:57] op_sel_hi:[1,0,1]
	v_pk_mul_f32 v[56:57], v[62:63], v[150:151]
	v_pk_fma_f32 v[64:65], v[174:175], s[2:3], v[54:55] op_sel_hi:[1,0,1]
	v_pk_fma_f32 v[54:55], v[186:187], s[2:3], v[30:31] op_sel_hi:[1,0,1]
	v_lshl_add_u64 v[30:31], v[162:163], 0, s[0:1]
	v_pk_fma_f32 v[62:63], v[172:173], s[2:3], v[56:57] op_sel_hi:[1,0,1]
	v_pk_fma_f32 v[58:59], v[182:183], s[2:3], v[38:39] op_sel_hi:[1,0,1]
	v_pk_fma_f32 v[60:61], v[184:185], s[2:3], v[40:41] op_sel_hi:[1,0,1]
	v_pk_fma_f32 v[56:57], v[188:189], s[2:3], v[32:33] op_sel_hi:[1,0,1]
	v_pk_mul_f32 v[32:33], v[50:51], v[138:139]
	global_load_dwordx4 v[162:165], v[30:31], off nt
	global_load_dwordx4 v[168:171], v[30:31], off offset:64 nt
	global_load_dwordx4 v[172:175], v[30:31], off offset:512 nt
	global_load_dwordx4 v[182:185], v[30:31], off offset:576 nt
	v_pk_mul_f32 v[30:31], v[52:53], v[140:141]
	v_pk_fma_f32 v[40:41], v[192:193], s[2:3], v[20:21] op_sel_hi:[1,0,1]
	v_pk_fma_f32 v[52:53], v[156:157], s[2:3], v[30:31] op_sel_hi:[1,0,1]
	v_pk_mul_f32 v[30:31], v[44:45], v[152:153]
	v_pk_fma_f32 v[50:51], v[154:155], s[2:3], v[32:33] op_sel_hi:[1,0,1]
	v_pk_fma_f32 v[44:45], v[160:161], s[2:3], v[30:31] op_sel_hi:[1,0,1]
	v_pk_fma_f32 v[30:31], v[194:195], s[2:3], v[14:15] op_sel_hi:[1,0,1]
	v_pk_mul_f32 v[14:15], v[136:137], v[140:141]
	v_pk_mul_f32 v[32:33], v[42:43], v[150:151]
	v_pk_fma_f32 v[38:39], v[190:191], s[2:3], v[18:19] op_sel_hi:[1,0,1]
	v_pk_fma_f32 v[42:43], v[158:159], s[2:3], v[32:33] op_sel_hi:[1,0,1]
	v_pk_fma_f32 v[32:33], v[196:197], s[2:3], v[16:17] op_sel_hi:[1,0,1]
	v_pk_mul_f32 v[16:17], v[134:135], v[138:139]
	v_mul_f32_e32 v134, v113, v113
	v_mul_f32_e32 v136, v3, v3
	v_cmp_eq_u32_e64 s[0:1], 0, v167
	s_waitcnt vmcnt(0) lgkmcnt(0)
	v_pk_fma_f32 v[20:21], v[164:165], s[2:3], v[14:15] op_sel_hi:[1,0,1]
	v_pk_mul_f32 v[14:15], v[130:131], v[150:151]
	v_and_b32_e32 v130, 64, v229
	v_add_u32_e32 v130, 64, v130
	v_cmp_lt_i32_e32 vcc, v0, v130
	v_xor_b32_e32 v131, 32, v229
	v_pk_fma_f32 v[18:19], v[162:163], s[2:3], v[16:17] op_sel_hi:[1,0,1]
	v_cndmask_b32_e32 v0, v229, v0, vcc
	v_cmp_lt_i32_e32 vcc, v131, v130
	v_pk_mul_f32 v[16:17], v[132:133], v[152:153]
	v_mov_b32_e32 v133, v113
	v_cndmask_b32_e32 v130, v229, v131, vcc
	v_lshlrev_b32_e32 v205, 2, v130
	v_add_f32_e32 v130, 0, v110
	v_add_f32_e32 v132, v111, v130
	v_mul_f32_e32 v130, v111, v111
	v_add_f32_e32 v132, v112, v132
	v_pk_fma_f32 v[130:131], v[110:111], v[110:111], v[130:131] op_sel_hi:[1,1,0]
	v_add_f32_e32 v132, v113, v132
	v_pk_fma_f32 v[130:131], v[112:113], v[112:113], v[130:131]
	v_add_f32_e32 v135, v106, v132
	v_mov_b32_e32 v132, v106
	v_pk_add_f32 v[130:131], v[134:135], v[130:131] op_sel_hi:[0,1]
	v_pk_fma_f32 v[130:131], v[132:133], v[132:133], v[130:131]
	v_add_f32_e32 v132, v107, v135
	v_add_f32_e32 v135, v108, v132
	v_mul_f32_e32 v134, v107, v107
	v_mov_b32_e32 v132, v108
	v_mov_b32_e32 v133, v107
	v_pk_add_f32 v[130:131], v[134:135], v[130:131] op_sel_hi:[0,1]
	v_pk_fma_f32 v[130:131], v[132:133], v[132:133], v[130:131]
	v_add_f32_e32 v132, v109, v135
	v_add_f32_e32 v135, v102, v132
	v_mul_f32_e32 v134, v109, v109
	v_mov_b32_e32 v132, v102
	v_mov_b32_e32 v133, v109
	v_pk_add_f32 v[130:131], v[134:135], v[130:131] op_sel_hi:[0,1]
	v_pk_fma_f32 v[130:131], v[132:133], v[132:133], v[130:131]
	v_add_f32_e32 v132, v103, v135
	v_add_f32_e32 v135, v104, v132
	v_mul_f32_e32 v134, v103, v103
	v_mov_b32_e32 v132, v104
	v_mov_b32_e32 v133, v103
	v_pk_add_f32 v[130:131], v[134:135], v[130:131] op_sel_hi:[0,1]
	v_pk_fma_f32 v[130:131], v[132:133], v[132:133], v[130:131]
	v_add_f32_e32 v132, v105, v135
	v_add_f32_e32 v135, v2, v132
	v_mul_f32_e32 v134, v105, v105
	v_mov_b32_e32 v132, v2
	v_mov_b32_e32 v133, v105
	v_pk_add_f32 v[130:131], v[134:135], v[130:131] op_sel_hi:[0,1]
	v_pk_fma_f32 v[130:131], v[132:133], v[132:133], v[130:131]
	v_add_f32_e32 v132, v3, v135
	v_mov_b32_e32 v134, v4
	v_mov_b32_e32 v135, v3
	v_pk_add_f32 v[130:131], v[136:137], v[130:131] op_sel_hi:[0,1]
	v_pk_fma_f32 v[130:131], v[134:135], v[134:135], v[130:131]
	v_pk_mul_f32 v[134:135], v[4:5], v[4:5]
	v_add_f32_e32 v132, v4, v132
	v_pk_mov_b32 v[130:131], v[4:5], v[130:131] op_sel:[1,0]
	v_mov_b32_e32 v133, v135
	v_lshlrev_b32_e32 v0, 2, v0
	v_pk_add_f32 v[130:131], v[130:131], v[132:133]
	ds_bpermute_b32 v132, v0, v130
	ds_bpermute_b32 v133, v0, v131
	v_pk_fma_f32 v[14:15], v[168:169], s[2:3], v[14:15] op_sel_hi:[1,0,1]
	v_pk_fma_f32 v[16:17], v[170:171], s[2:3], v[16:17] op_sel_hi:[1,0,1]
	v_pk_fma_f32 v[10:11], v[172:173], s[2:3], v[10:11] op_sel_hi:[1,0,1]
	v_pk_fma_f32 v[12:13], v[174:175], s[2:3], v[12:13] op_sel_hi:[1,0,1]
	s_waitcnt lgkmcnt(0)
	v_pk_add_f32 v[130:131], v[130:131], v[132:133]
	ds_bpermute_b32 v132, v205, v130
	ds_bpermute_b32 v133, v205, v131
	v_pk_fma_f32 v[6:7], v[182:183], s[2:3], v[6:7] op_sel_hi:[1,0,1]
	v_pk_fma_f32 v[8:9], v[184:185], s[2:3], v[8:9] op_sel_hi:[1,0,1]
	s_lshl_b32 s2, s9, 3
	s_add_i32 s23, s2, 0
	s_and_saveexec_b64 s[2:3], s[0:1]
	s_cbranch_execz .LBB0_1787
	s_lshl_b32 s4, s28, 11
	s_add_i32 s4, s23, s4
	v_lshl_add_u32 v134, v204, 5, s4
	s_waitcnt lgkmcnt(0)
	v_pk_add_f32 v[130:131], v[130:131], v[132:133]
	ds_write_b64 v134, v[130:131]

;   DI void fused(AccT& acc, const Unit& u, LAS unsigned char* lds, int tid, int wr, int wc, int fr, int fq) const {
;     ...
;     const int row0 = u.pm * BM + wr * 64 + fr, col0 = u.pn * BM + wc * 32 + 4 * fq, b = (u.pm * BM) >> 12;
;     { f32x4 g[2][2], xc[2][2], xn[2][2];
; #pragma unroll
;       for (int bj = 0; bj < 2; ++bj)
; #pragma unroll
;         for (int n = 0; n < 2; ++n) g[bj][n] = *(const f32x4*)(gv + b * 12288 + col0 + bj * HALF + n * 16);
;       { const float* xr = xin + (size_t)row0 * DM + col0;
; #pragma unroll
;         for (int bj = 0; bj < 2; ++bj)
; #pragma unroll
;           for (int n = 0; n < 2; ++n) xc[bj][n] = __builtin_nontemporal_load((const f32x4*)(xr + bj * HALF + n * 16)); }
; #pragma unroll
;       for (int k = 0; k < 8; ++k) { const int ai = k >> 2, m = k & 3;
;         if (k < 7) { const int k1 = k + 1; const float* xr = xin + (size_t)(row0 + (k1 >> 2) * HALF + (k1 & 3) * 16) * DM + col0; asm volatile("" : "+v"(xr));
; #pragma unroll
;           for (int bj = 0; bj < 2; ++bj)
; #pragma unroll
;             for (int n = 0; n < 2; ++n) xn[bj][n] = __builtin_nontemporal_load((const f32x4*)(xr + bj * HALF + n * 16)); }
; #pragma unroll
;         for (int bj = 0; bj < 2; ++bj)
; #pragma unroll
;           for (int n = 0; n < 2; ++n)
; #pragma unroll
;             for (int j = 0; j < 4; ++j) acc[ai][bj][m][n][j] = ALPHA * xc[bj][n][j] + g[bj][n][j] * acc[ai][bj][m][n][j];
;         asm volatile("" :: "v"(acc[ai][0][m][0]), "v"(acc[ai][0][m][1]), "v"(acc[ai][1][m][0]), "v"(acc[ai][1][m][1]));
; #pragma unroll
;         for (int bj = 0; bj < 2; ++bj)
; #pragma unroll
;           for (int n = 0; n < 2; ++n) xc[bj][n] = xn[bj][n]; } }
.LBB0_1998:
	s_lshl_b32 s0, s9, 5
	s_lshl_b32 s1, s10, 8
	s_or_b32 s0, s1, s0
	v_lshl_or_b32 v198, v166, 2, s0
	s_lshr_b32 s0, s8, 4
	s_mulk_i32 s0, 0x3000
	s_lshl_b32 s23, s8, 8
	s_ashr_i32 s1, s0, 31
	s_add_i32 s2, s23, s34
	s_lshl_b64 s[12:13], s[0:1], 2
	s_add_u32 s0, s26, s12
	v_ashrrev_i32_e32 v199, 31, v198
	s_addc_u32 s1, s27, s13
	v_lshlrev_b64 v[200:201], 2, v[198:199]
	v_lshl_add_u64 v[122:123], s[0:1], 0, v[200:201]
	s_mov_b64 s[0:1], 0xa000
	v_lshl_add_u64 v[124:125], v[122:123], 0, s[0:1]
	s_mov_b32 s0, 0xa000
	v_add_co_u32_e32 v122, vcc, s0, v122
	v_or_b32_e32 v164, s2, v222
	s_nop 0
	v_addc_co_u32_e32 v123, vcc, 0, v123, vcc
	v_ashrrev_i32_e32 v165, 31, v164
	v_readlane_b32 s0, v251, 26
	s_barrier
	global_load_dwordx4 v[138:141], v[122:123], off
	global_load_dwordx4 v[150:153], v[124:125], off offset:64
	global_load_dwordx4 v[146:149], v[124:125], off offset:512
	global_load_dwordx4 v[142:145], v[124:125], off offset:576
	v_lshlrev_b64 v[122:123], 13, v[164:165]
	v_readlane_b32 s1, v251, 27
	v_or_b32_e32 v168, 16, v164
	v_ashrrev_i32_e32 v169, 31, v168
	v_lshl_add_u64 v[122:123], s[0:1], 0, v[122:123]
	v_lshl_add_u64 v[162:163], v[122:123], 0, v[200:201]
	global_load_dwordx4 v[122:125], v[162:163], off nt
	global_load_dwordx4 v[126:129], v[162:163], off offset:64 nt
	global_load_dwordx4 v[154:157], v[162:163], off offset:512 nt
	global_load_dwordx4 v[158:161], v[162:163], off offset:576 nt
	v_lshlrev_b64 v[168:169], 13, v[168:169]
	v_lshl_add_u64 v[168:169], s[0:1], 0, v[168:169]
	v_lshl_add_u64 v[180:181], v[168:169], 0, v[200:201]
	global_load_dwordx4 v[168:171], v[180:181], off nt
	global_load_dwordx4 v[172:175], v[180:181], off offset:64 nt
	global_load_dwordx4 v[176:179], v[180:181], off offset:512 nt
	s_nop 0
	global_load_dwordx4 v[180:183], v[180:181], off offset:576 nt
	s_mov_b32 s2, 0x3fb504f3
	v_xor_b32_e32 v0, 16, v229
	s_waitcnt vmcnt(4)
	v_pk_mul_f32 v[2:3], v[2:3], v[138:139]
	v_pk_mul_f32 v[4:5], v[4:5], v[140:141]
	v_pk_mul_f32 v[8:9], v[8:9], v[152:153]
	v_pk_mul_f32 v[6:7], v[6:7], v[150:151]
	v_pk_mul_f32 v[12:13], v[12:13], v[148:149]
	v_pk_mul_f32 v[10:11], v[10:11], v[146:147]
	v_pk_mul_f32 v[16:17], v[16:17], v[144:145]
	v_pk_fma_f32 v[2:3], v[122:123], s[2:3], v[2:3] op_sel_hi:[1,0,1]
	v_or_b32_e32 v122, 32, v164
	v_ashrrev_i32_e32 v123, 31, v122
	v_lshlrev_b64 v[122:123], 13, v[122:123]
	v_lshl_add_u64 v[122:123], s[0:1], 0, v[122:123]
	v_pk_mul_f32 v[14:15], v[14:15], v[142:143]
	v_lshl_add_u64 v[122:123], v[122:123], 0, v[200:201]
	v_or_b32_e32 v164, 48, v164
	v_pk_fma_f32 v[4:5], v[124:125], s[2:3], v[4:5] op_sel_hi:[1,0,1]
	v_pk_fma_f32 v[6:7], v[126:127], s[2:3], v[6:7] op_sel_hi:[1,0,1]
	v_pk_fma_f32 v[8:9], v[128:129], s[2:3], v[8:9] op_sel_hi:[1,0,1]
	v_pk_fma_f32 v[10:11], v[154:155], s[2:3], v[10:11] op_sel_hi:[1,0,1]
	v_pk_fma_f32 v[12:13], v[156:157], s[2:3], v[12:13] op_sel_hi:[1,0,1]
	v_pk_fma_f32 v[14:15], v[158:159], s[2:3], v[14:15] op_sel_hi:[1,0,1]
	v_pk_fma_f32 v[16:17], v[160:161], s[2:3], v[16:17] op_sel_hi:[1,0,1]
	v_ashrrev_i32_e32 v165, 31, v164
	global_load_dwordx4 v[158:161], v[122:123], off nt
	global_load_dwordx4 v[154:157], v[122:123], off offset:64 nt
	global_load_dwordx4 v[126:129], v[122:123], off offset:512 nt
	s_nop 0
	global_load_dwordx4 v[122:125], v[122:123], off offset:576 nt
	v_lshlrev_b64 v[164:165], 13, v[164:165]
	v_lshl_add_u64 v[164:165], s[0:1], 0, v[164:165]
	v_pk_mul_f32 v[28:29], v[28:29], v[140:141]
	v_pk_mul_f32 v[26:27], v[26:27], v[138:139]
	v_pk_mul_f32 v[32:33], v[32:33], v[152:153]
	v_pk_mul_f32 v[30:31], v[30:31], v[150:151]
	v_pk_mul_f32 v[24:25], v[24:25], v[148:149]
	v_pk_mul_f32 v[22:23], v[22:23], v[146:147]
	v_pk_mul_f32 v[20:21], v[20:21], v[144:145]
	v_pk_mul_f32 v[18:19], v[18:19], v[142:143]
	v_lshl_add_u64 v[164:165], v[164:165], 0, v[200:201]
	s_waitcnt vmcnt(4) lgkmcnt(0)
	v_pk_fma_f32 v[26:27], v[168:169], s[2:3], v[26:27] op_sel_hi:[1,0,1]
	v_pk_fma_f32 v[28:29], v[170:171], s[2:3], v[28:29] op_sel_hi:[1,0,1]
	v_pk_fma_f32 v[30:31], v[172:173], s[2:3], v[30:31] op_sel_hi:[1,0,1]
	v_pk_fma_f32 v[32:33], v[174:175], s[2:3], v[32:33] op_sel_hi:[1,0,1]
	v_pk_fma_f32 v[22:23], v[176:177], s[2:3], v[22:23] op_sel_hi:[1,0,1]
	v_pk_fma_f32 v[24:25], v[178:179], s[2:3], v[24:25] op_sel_hi:[1,0,1]
	v_pk_fma_f32 v[18:19], v[180:181], s[2:3], v[18:19] op_sel_hi:[1,0,1]
	v_pk_fma_f32 v[20:21], v[182:183], s[2:3], v[20:21] op_sel_hi:[1,0,1]
	v_pk_mul_f32 v[42:43], v[42:43], v[150:151]
	global_load_dwordx4 v[168:171], v[164:165], off nt
	global_load_dwordx4 v[172:175], v[164:165], off offset:64 nt
	global_load_dwordx4 v[176:179], v[164:165], off offset:512 nt
	global_load_dwordx4 v[180:183], v[164:165], off offset:576 nt
	s_mov_b64 s[0:1], 0x100000
	v_pk_mul_f32 v[48:49], v[48:49], v[140:141]
	v_pk_mul_f32 v[46:47], v[46:47], v[138:139]
	v_pk_mul_f32 v[44:45], v[44:45], v[152:153]
	v_pk_mul_f32 v[40:41], v[40:41], v[148:149]
	v_pk_mul_f32 v[38:39], v[38:39], v[146:147]
	v_pk_mul_f32 v[36:37], v[36:37], v[144:145]
	v_pk_mul_f32 v[34:35], v[34:35], v[142:143]
	v_pk_mul_f32 v[64:65], v[64:65], v[140:141]
	v_pk_mul_f32 v[62:63], v[62:63], v[138:139]
	v_pk_mul_f32 v[60:61], v[60:61], v[152:153]
	v_pk_mul_f32 v[58:59], v[58:59], v[150:151]
	v_pk_mul_f32 v[56:57], v[56:57], v[148:149]
	v_pk_mul_f32 v[54:55], v[54:55], v[146:147]
	v_pk_mul_f32 v[52:53], v[52:53], v[144:145]
	v_pk_mul_f32 v[50:51], v[50:51], v[142:143]
	v_pk_mul_f32 v[114:115], v[114:115], v[150:151]
	v_pk_mul_f32 v[98:99], v[98:99], v[142:143]
	v_pk_mul_f32 v[120:121], v[120:121], v[140:141]
	v_pk_mul_f32 v[118:119], v[118:119], v[138:139]
	v_pk_mul_f32 v[116:117], v[116:117], v[152:153]
	v_pk_mul_f32 v[104:105], v[104:105], v[148:149]
	v_pk_mul_f32 v[102:103], v[102:103], v[146:147]
	v_pk_mul_f32 v[100:101], v[100:101], v[144:145]
	v_pk_mul_f32 v[82:83], v[82:83], v[142:143]
	v_pk_mul_f32 v[88:89], v[88:89], v[148:149]
	v_pk_mul_f32 v[86:87], v[86:87], v[146:147]
	v_pk_mul_f32 v[84:85], v[84:85], v[144:145]
	v_pk_mul_f32 v[74:75], v[74:75], v[142:143]
	v_pk_mul_f32 v[80:81], v[80:81], v[148:149]
	v_pk_mul_f32 v[76:77], v[76:77], v[144:145]
	v_pk_mul_f32 v[78:79], v[78:79], v[146:147]
	v_pk_mul_f32 v[72:73], v[72:73], v[148:149]
	v_pk_mul_f32 v[70:71], v[70:71], v[146:147]
	v_pk_mul_f32 v[68:69], v[68:69], v[144:145]
	v_pk_mul_f32 v[66:67], v[66:67], v[142:143]
	s_waitcnt vmcnt(4)
;   DI void fused(AccT& acc, const Unit& u, LAS unsigned char* lds, int tid, int wr, int wc, int fr, int fq) const {
;     ...
;       for (int k = 0; k < 8; ++k) { const int ai = k >> 2, m = k & 3;
;         if (k < 7) { const int k1 = k + 1; const float* xr = xin + (size_t)(row0 + (k1 >> 2) * HALF + (k1 & 3) * 16) * DM + col0; asm volatile("" : "+v"(xr));
; #pragma unroll
;           for (int bj = 0; bj < 2; ++bj)
; #pragma unroll
;             for (int n = 0; n < 2; ++n) xn[bj][n] = __builtin_nontemporal_load((const f32x4*)(xr + bj * HALF + n * 16)); }
; #pragma unroll
;         for (int bj = 0; bj < 2; ++bj)
; #pragma unroll
;           for (int n = 0; n < 2; ++n)
; #pragma unroll
;             for (int j = 0; j < 4; ++j) acc[ai][bj][m][n][j] = ALPHA * xc[bj][n][j] + g[bj][n][j] * acc[ai][bj][m][n][j];
;         asm volatile("" :: "v"(acc[ai][0][m][0]), "v"(acc[ai][0][m][1]), "v"(acc[ai][1][m][0]), "v"(acc[ai][1][m][1]));
; #pragma unroll
;         for (int bj = 0; bj < 2; ++bj)
; #pragma unroll
;           for (int n = 0; n < 2; ++n) xc[bj][n] = xn[bj][n]; } }
	v_pk_fma_f32 v[46:47], v[158:159], s[2:3], v[46:47] op_sel_hi:[1,0,1]
	v_pk_fma_f32 v[42:43], v[154:155], s[2:3], v[42:43] op_sel_hi:[1,0,1]
	v_lshl_add_u64 v[154:155], v[162:163], 0, s[0:1]
	v_pk_fma_f32 v[48:49], v[160:161], s[2:3], v[48:49] op_sel_hi:[1,0,1]
	v_pk_fma_f32 v[44:45], v[156:157], s[2:3], v[44:45] op_sel_hi:[1,0,1]
	v_pk_fma_f32 v[38:39], v[126:127], s[2:3], v[38:39] op_sel_hi:[1,0,1]
	v_pk_fma_f32 v[40:41], v[128:129], s[2:3], v[40:41] op_sel_hi:[1,0,1]
	v_pk_fma_f32 v[34:35], v[122:123], s[2:3], v[34:35] op_sel_hi:[1,0,1]
	v_pk_fma_f32 v[36:37], v[124:125], s[2:3], v[36:37] op_sel_hi:[1,0,1]
	s_mov_b64 s[0:1], 0x120000
	global_load_dwordx4 v[126:129], v[154:155], off nt
	global_load_dwordx4 v[122:125], v[154:155], off offset:64 nt
	global_load_dwordx4 v[158:161], v[154:155], off offset:512 nt
	s_nop 0
	global_load_dwordx4 v[154:157], v[154:155], off offset:576 nt
	v_lshl_add_u64 v[164:165], v[162:163], 0, s[0:1]
	s_mov_b64 s[0:1], 0x140000
	s_waitcnt vmcnt(4) lgkmcnt(0)
	v_pk_fma_f32 v[62:63], v[168:169], s[2:3], v[62:63] op_sel_hi:[1,0,1]
	v_pk_fma_f32 v[64:65], v[170:171], s[2:3], v[64:65] op_sel_hi:[1,0,1]
	v_pk_fma_f32 v[58:59], v[172:173], s[2:3], v[58:59] op_sel_hi:[1,0,1]
	v_pk_fma_f32 v[60:61], v[174:175], s[2:3], v[60:61] op_sel_hi:[1,0,1]
	v_pk_fma_f32 v[54:55], v[176:177], s[2:3], v[54:55] op_sel_hi:[1,0,1]
	v_pk_fma_f32 v[56:57], v[178:179], s[2:3], v[56:57] op_sel_hi:[1,0,1]
	v_pk_fma_f32 v[50:51], v[180:181], s[2:3], v[50:51] op_sel_hi:[1,0,1]
	v_pk_fma_f32 v[52:53], v[182:183], s[2:3], v[52:53] op_sel_hi:[1,0,1]
	s_waitcnt vmcnt(0)
	v_pk_fma_f32 v[126:127], v[126:127], s[2:3], v[118:119] op_sel_hi:[1,0,1]
	global_load_dwordx4 v[168:171], v[164:165], off nt
	global_load_dwordx4 v[172:175], v[164:165], off offset:64 nt
	global_load_dwordx4 v[176:179], v[164:165], off offset:512 nt
	global_load_dwordx4 v[180:183], v[164:165], off offset:576 nt
	v_pk_fma_f32 v[122:123], v[122:123], s[2:3], v[114:115] op_sel_hi:[1,0,1]
	v_pk_fma_f32 v[114:115], v[154:155], s[2:3], v[98:99] op_sel_hi:[1,0,1]
	v_lshl_add_u64 v[98:99], v[162:163], 0, s[0:1]
	v_pk_fma_f32 v[128:129], v[128:129], s[2:3], v[120:121] op_sel_hi:[1,0,1]
	v_pk_fma_f32 v[124:125], v[124:125], s[2:3], v[116:117] op_sel_hi:[1,0,1]
	v_pk_fma_f32 v[118:119], v[158:159], s[2:3], v[102:103] op_sel_hi:[1,0,1]
	v_pk_fma_f32 v[120:121], v[160:161], s[2:3], v[104:105] op_sel_hi:[1,0,1]
	v_pk_fma_f32 v[116:117], v[156:157], s[2:3], v[100:101] op_sel_hi:[1,0,1]
	v_pk_mul_f32 v[100:101], v[110:111], v[138:139]
	global_load_dwordx4 v[154:157], v[98:99], off nt
	global_load_dwordx4 v[158:161], v[98:99], off offset:64 nt
	global_load_dwordx4 v[184:187], v[98:99], off offset:512 nt
	global_load_dwordx4 v[188:191], v[98:99], off offset:576 nt
	v_pk_mul_f32 v[98:99], v[112:113], v[140:141]
	s_mov_b64 s[0:1], 0x160000
	s_waitcnt vmcnt(0) lgkmcnt(0)
	v_pk_fma_f32 v[112:113], v[170:171], s[2:3], v[98:99] op_sel_hi:[1,0,1]
	v_pk_mul_f32 v[98:99], v[108:109], v[152:153]
	v_pk_fma_f32 v[110:111], v[168:169], s[2:3], v[100:101] op_sel_hi:[1,0,1]
	v_pk_mul_f32 v[100:101], v[106:107], v[150:151]
	v_pk_fma_f32 v[108:109], v[174:175], s[2:3], v[98:99] op_sel_hi:[1,0,1]
	v_pk_fma_f32 v[98:99], v[180:181], s[2:3], v[82:83] op_sel_hi:[1,0,1]
	v_lshl_add_u64 v[82:83], v[162:163], 0, s[0:1]
	v_pk_fma_f32 v[106:107], v[172:173], s[2:3], v[100:101] op_sel_hi:[1,0,1]
	v_pk_fma_f32 v[102:103], v[176:177], s[2:3], v[86:87] op_sel_hi:[1,0,1]
	v_pk_fma_f32 v[104:105], v[178:179], s[2:3], v[88:89] op_sel_hi:[1,0,1]
	v_pk_fma_f32 v[100:101], v[182:183], s[2:3], v[84:85] op_sel_hi:[1,0,1]
	v_pk_mul_f32 v[84:85], v[94:95], v[138:139]
	global_load_dwordx4 v[162:165], v[82:83], off nt
	global_load_dwordx4 v[168:171], v[82:83], off offset:64 nt
	global_load_dwordx4 v[172:175], v[82:83], off offset:512 nt
	global_load_dwordx4 v[176:179], v[82:83], off offset:576 nt
	v_pk_mul_f32 v[82:83], v[96:97], v[140:141]
	v_pk_fma_f32 v[88:89], v[186:187], s[2:3], v[80:81] op_sel_hi:[1,0,1]
	v_pk_fma_f32 v[96:97], v[156:157], s[2:3], v[82:83] op_sel_hi:[1,0,1]
	v_pk_mul_f32 v[82:83], v[92:93], v[152:153]
	v_pk_fma_f32 v[94:95], v[154:155], s[2:3], v[84:85] op_sel_hi:[1,0,1]
	v_pk_fma_f32 v[92:93], v[160:161], s[2:3], v[82:83] op_sel_hi:[1,0,1]
	v_pk_fma_f32 v[82:83], v[188:189], s[2:3], v[74:75] op_sel_hi:[1,0,1]
	v_pk_mul_f32 v[74:75], v[136:137], v[140:141]
	v_pk_mul_f32 v[84:85], v[90:91], v[150:151]
	v_pk_fma_f32 v[86:87], v[184:185], s[2:3], v[78:79] op_sel_hi:[1,0,1]
	v_pk_fma_f32 v[90:91], v[158:159], s[2:3], v[84:85] op_sel_hi:[1,0,1]
	v_pk_fma_f32 v[84:85], v[190:191], s[2:3], v[76:77] op_sel_hi:[1,0,1]
	v_pk_mul_f32 v[76:77], v[134:135], v[138:139]
	v_mul_f32_e32 v134, v5, v5
	v_mul_f32_e32 v136, v15, v15
	v_cmp_eq_u32_e64 s[0:1], 0, v166
	s_waitcnt vmcnt(0) lgkmcnt(0)
; #define LAS __attribute__((address_space(3)))
; DI void ln_exchange(const AccT& acc, LAS float* red, float* stats, unsigned* cnt, int pm, int pn, int tid, int wr, int wc, int fr, int fq) {
; #pragma unroll
;   for (int ai = 0; ai < 2; ++ai)
; #pragma unroll
;     for (int m = 0; m < 4; ++m) {
;       float s1 = 0.f, s2 = 0.f;
; #pragma unroll
;       for (int bj = 0; bj < 2; ++bj)
; #pragma unroll
;         for (int n = 0; n < 2; ++n)
; #pragma unroll
;           for (int j = 0; j < 4; ++j) { const float x = acc[ai][bj][m][n][j]; s1 += x; s2 += x * x; }
;       s1 += __shfl_xor(s1, 16); s2 += __shfl_xor(s2, 16); s1 += __shfl_xor(s1, 32); s2 += __shfl_xor(s2, 32);
;       if (fq == 0) { const int rl = ai * 128 + wr * 64 + m * 16 + fr; red[(rl * 4 + wc) * 2] = s1; red[(rl * 4 + wc) * 2 + 1] = s2; }
;   DI void fused(AccT& acc, const Unit& u, LAS unsigned char* lds, int tid, int wr, int wc, int fr, int fq) const {
;     ...
;       for (int k = 0; k < 8; ++k) { const int ai = k >> 2, m = k & 3;
;         if (k < 7) { const int k1 = k + 1; const float* xr = xin + (size_t)(row0 + (k1 >> 2) * HALF + (k1 & 3) * 16) * DM + col0; asm volatile("" : "+v"(xr));
; #pragma unroll
;           for (int bj = 0; bj < 2; ++bj)
; #pragma unroll
;             for (int n = 0; n < 2; ++n) xn[bj][n] = __builtin_nontemporal_load((const f32x4*)(xr + bj * HALF + n * 16)); }
; #pragma unroll
;         for (int bj = 0; bj < 2; ++bj)
; #pragma unroll
;           for (int n = 0; n < 2; ++n)
; #pragma unroll
;             for (int j = 0; j < 4; ++j) acc[ai][bj][m][n][j] = ALPHA * xc[bj][n][j] + g[bj][n][j] * acc[ai][bj][m][n][j];
;         asm volatile("" :: "v"(acc[ai][0][m][0]), "v"(acc[ai][0][m][1]), "v"(acc[ai][1][m][0]), "v"(acc[ai][1][m][1]));
; #pragma unroll
;         for (int bj = 0; bj < 2; ++bj)
; #pragma unroll
;           for (int n = 0; n < 2; ++n) xc[bj][n] = xn[bj][n]; } }
	v_pk_fma_f32 v[80:81], v[164:165], s[2:3], v[74:75] op_sel_hi:[1,0,1]
	v_pk_mul_f32 v[74:75], v[130:131], v[150:151]
	v_and_b32_e32 v130, 64, v229
	v_add_u32_e32 v130, 64, v130
	v_cmp_lt_i32_e32 vcc, v0, v130
	v_xor_b32_e32 v131, 32, v229
	v_pk_fma_f32 v[78:79], v[162:163], s[2:3], v[76:77] op_sel_hi:[1,0,1]
	v_cndmask_b32_e32 v0, v229, v0, vcc
	v_cmp_lt_i32_e32 vcc, v131, v130
	v_pk_mul_f32 v[76:77], v[132:133], v[152:153]
	v_mov_b32_e32 v133, v5
	v_cndmask_b32_e32 v130, v229, v131, vcc
	v_lshlrev_b32_e32 v223, 2, v130
	v_add_f32_e32 v130, 0, v2
	v_add_f32_e32 v132, v3, v130
	v_mul_f32_e32 v130, v3, v3
	v_add_f32_e32 v132, v4, v132
	v_pk_fma_f32 v[130:131], v[2:3], v[2:3], v[130:131] op_sel_hi:[1,1,0]
	v_add_f32_e32 v132, v5, v132
	v_pk_fma_f32 v[130:131], v[4:5], v[4:5], v[130:131]
	v_add_f32_e32 v135, v6, v132
	v_mov_b32_e32 v132, v6
	v_pk_add_f32 v[130:131], v[134:135], v[130:131] op_sel_hi:[0,1]
	v_pk_fma_f32 v[130:131], v[132:133], v[132:133], v[130:131]
	v_add_f32_e32 v132, v7, v135
	v_add_f32_e32 v135, v8, v132
	v_mul_f32_e32 v134, v7, v7
	v_mov_b32_e32 v132, v8
	v_mov_b32_e32 v133, v7
	v_pk_add_f32 v[130:131], v[134:135], v[130:131] op_sel_hi:[0,1]
	v_pk_fma_f32 v[130:131], v[132:133], v[132:133], v[130:131]
	v_add_f32_e32 v132, v9, v135
	v_add_f32_e32 v135, v10, v132
	v_mul_f32_e32 v134, v9, v9
	v_mov_b32_e32 v132, v10
	v_mov_b32_e32 v133, v9
	v_pk_add_f32 v[130:131], v[134:135], v[130:131] op_sel_hi:[0,1]
	v_pk_fma_f32 v[130:131], v[132:133], v[132:133], v[130:131]
	v_add_f32_e32 v132, v11, v135
	v_add_f32_e32 v135, v12, v132
	v_mul_f32_e32 v134, v11, v11
	v_mov_b32_e32 v132, v12
	v_mov_b32_e32 v133, v11
	v_pk_add_f32 v[130:131], v[134:135], v[130:131] op_sel_hi:[0,1]
	v_pk_fma_f32 v[130:131], v[132:133], v[132:133], v[130:131]
	v_add_f32_e32 v132, v13, v135
	v_add_f32_e32 v135, v14, v132
	v_mul_f32_e32 v134, v13, v13
	v_mov_b32_e32 v132, v14
	v_mov_b32_e32 v133, v13
	v_pk_add_f32 v[130:131], v[134:135], v[130:131] op_sel_hi:[0,1]
	v_pk_fma_f32 v[130:131], v[132:133], v[132:133], v[130:131]
	v_add_f32_e32 v132, v15, v135
	v_mov_b32_e32 v134, v16
	v_mov_b32_e32 v135, v15
	v_pk_add_f32 v[130:131], v[136:137], v[130:131] op_sel_hi:[0,1]
	v_pk_fma_f32 v[130:131], v[134:135], v[134:135], v[130:131]
	v_pk_mul_f32 v[134:135], v[16:17], v[16:17]
	v_add_f32_e32 v132, v16, v132
	v_pk_mov_b32 v[130:131], v[16:17], v[130:131] op_sel:[1,0]
	v_mov_b32_e32 v133, v135
	v_lshlrev_b32_e32 v0, 2, v0
	v_pk_add_f32 v[130:131], v[130:131], v[132:133]
	ds_bpermute_b32 v132, v0, v130
	ds_bpermute_b32 v133, v0, v131
	v_pk_fma_f32 v[74:75], v[168:169], s[2:3], v[74:75] op_sel_hi:[1,0,1]
	v_pk_fma_f32 v[76:77], v[170:171], s[2:3], v[76:77] op_sel_hi:[1,0,1]
	v_pk_fma_f32 v[70:71], v[172:173], s[2:3], v[70:71] op_sel_hi:[1,0,1]
	v_pk_fma_f32 v[72:73], v[174:175], s[2:3], v[72:73] op_sel_hi:[1,0,1]
	s_waitcnt lgkmcnt(0)
	v_pk_add_f32 v[130:131], v[130:131], v[132:133]
	ds_bpermute_b32 v132, v223, v130
	ds_bpermute_b32 v133, v223, v131
	v_pk_fma_f32 v[66:67], v[176:177], s[2:3], v[66:67] op_sel_hi:[1,0,1]
	v_pk_fma_f32 v[68:69], v[178:179], s[2:3], v[68:69] op_sel_hi:[1,0,1]
	s_lshl_b32 s2, s9, 3
	s_add_i32 s24, s2, 0
	s_and_saveexec_b64 s[2:3], s[0:1]
	s_mov_b32 s27, 0x800000
	s_cbranch_execz .LBB0_2000
	s_lshl_b32 s4, s22, 11
	s_add_i32 s4, s24, s4
	v_lshl_add_u32 v134, v222, 5, s4
	s_waitcnt lgkmcnt(0)
	v_pk_add_f32 v[130:131], v[130:131], v[132:133]
	ds_write_b64 v134, v[130:131]
